# P9 row-panel partial sums reduced cooperatively in one load batch; grid barrier leaders no longer post the unused per-XCD release word
# baseline (speedup 1.0000x reference)
; __device__ __forceinline__ unsigned xb_add(unsigned* p, unsigned v) { return __hip_atomic_fetch_add(p, v, __ATOMIC_RELAXED, __HIP_MEMORY_SCOPE_AGENT); }
; __device__ __forceinline__ void xcd_barrier(const XcdBarrier& b) {
;     ...
;             __builtin_amdgcn_fence(__ATOMIC_ACQUIRE, "agent");
;             xb_add(&bar[XB_XGEN(b.x)], 1u);
;             asm volatile("s_waitcnt vmcnt(0)" ::: "memory");
.LBB0_135:
	s_or_b64 exec, exec, s[6:7]
	v_mov_b32_e32 v1, 0x2000
	v_mov_b32_e32 v2, 1
	s_waitcnt vmcnt(0)
	buffer_inv sc1
	s_waitcnt vmcnt(0)
